# baseline (speedup 1.0000x reference)
; #define SCHED() __builtin_amdgcn_sched_barrier(0)
; #define DSR(dst, addr, off) asm volatile("ds_read_b128 %0, %1 offset:%2" : "=&v"(dst) : "v"(addr), "n"(off) : "memory")
; #define LGKM(n) asm volatile("s_waitcnt lgkmcnt(%0)" ::"n"(n) : "memory")
; #define DSR(dst, addr, off) asm volatile("ds_read_b128 %0, %1 offset:%2" : "=&v"(dst) : "v"(addr), "n"(off) : "memory")
; #define LGKM(n) asm volatile("s_waitcnt lgkmcnt(%0)" ::"n"(n) : "memory")
; __device__ __forceinline__ void attn_phase(char* shm, const Params& p, const u16* __restrict__ qb, const u16* __restrict__ kb,
;                                            const u16* __restrict__ vT, u16* __restrict__ attn) {
;     ...
;         const float df = (float)(kt * 64 + u * 32 + 4 * hh - qpos);
;         bf16x8 P[2][2];
;         bf16x8 kf[2], qf[2];
;         DSR(kf[0], kb_ + kL0, u * 8192); DSR(qf[0], qaddr, 0);
; #pragma unroll
;         for (int c = 0; c < 2; ++c) {
;           f32x16 Sx;
; #pragma unroll
;           for (int i = 0; i < 16; ++i) Sx[i] = -sl2 * fabsf(df + (float)((i & 3) + 8 * (i >> 2)));
; #pragma unroll
;           for (int ks = 0; ks < 4; ++ks) {
;             const int f = c * 4 + ks;
;             if (f < 7) {
;               DSR(kf[(f + 1) & 1], kb_ + (kL0 ^ ((((f + 1) >> 2) * 8 + ((f + 1) & 3) * 2) << 4)), u * 8192);
;               DSR(qf[(f + 1) & 1], qaddr, (f + 1) * 1024);
;               LGKM(2);
;             } else LGKM(0);
;             SCHED();
;             Sx = __builtin_amdgcn_mfma_f32_32x32x16_bf16(kf[f & 1], qf[f & 1], Sx, 0, 0, 0);
;             SCHED();
;           }
;           float pv[16];
; #pragma unroll
;           for (int i = 0; i < 16; ++i) { pv[i] = __builtin_amdgcn_exp2f(Sx[i]); lsum[c] += pv[i]; }
; #pragma unroll
;           for (int a = 0; a < 2; ++a) {
;             i32x4 t4;
; #pragma unroll
;             for (int i = 0; i < 4; ++i) t4[i] = pk_bf16(pv[a * 8 + 2 * i], pv[a * 8 + 2 * i + 1]);
;             P[c][a] = __builtin_bit_cast(bf16x8, t4);
;           }
;         }
.LBB0_299:
	v_cvt_f32_i32_e32 v128, v205
	v_add_u32_e32 v160, s44, v188
	ds_read_b128 v[206:209], v160 offset:0
	ds_read_b128 v[210:213], v185 offset:0
	v_add_u32_e32 v214, s44, v190
	ds_read_b128 v[218:221], v214 offset:0
	ds_read_b128 v[222:225], v185 offset:0x400
	v_add_u32_e32 v215, s44, v191
	ds_read_b128 v[242:245], v215 offset:0
	ds_read_b128 v[246:249], v185 offset:0x800
	v_add_f32_e32 v129, 1.0, v128
	v_pk_add_f32 v[130:131], v[128:129], s[12:13] op_sel_hi:[0,1]
	v_pk_add_f32 v[132:133], v[128:129], s[14:15] op_sel_hi:[0,1]
	v_pk_add_f32 v[134:135], v[128:129], s[20:21] op_sel_hi:[0,1]
	v_pk_add_f32 v[136:137], v[128:129], s[22:23] op_sel_hi:[0,1]
	v_pk_add_f32 v[138:139], v[128:129], s[24:25] op_sel_hi:[0,1]
	v_pk_add_f32 v[140:141], v[128:129], s[26:27] op_sel_hi:[0,1]
	v_pk_add_f32 v[142:143], v[128:129], s[28:29] op_sel_hi:[0,1]
	v_and_b32_e32 v131, 0x7fffffff, v131
	v_and_b32_e32 v130, 0x7fffffff, v130
	v_and_b32_e32 v133, 0x7fffffff, v133
	v_and_b32_e32 v132, 0x7fffffff, v132
	v_and_b32_e32 v135, 0x7fffffff, v135
	v_and_b32_e32 v134, 0x7fffffff, v134
	v_and_b32_e32 v137, 0x7fffffff, v137
	v_and_b32_e32 v136, 0x7fffffff, v136
	v_and_b32_e32 v139, 0x7fffffff, v139
	v_and_b32_e32 v138, 0x7fffffff, v138
	v_and_b32_e32 v141, 0x7fffffff, v141
	v_and_b32_e32 v140, 0x7fffffff, v140
	v_and_b32_e32 v143, 0x7fffffff, v143
	v_and_b32_e32 v142, 0x7fffffff, v142
	v_and_b32_e32 v128, 0x7fffffff, v128
	v_and_b32_e32 v129, 0x7fffffff, v129
	s_add_i32 s0, s44, 0x4000
	v_pk_mul_f32 v[142:143], v[178:179], v[142:143]
	v_pk_mul_f32 v[140:141], v[178:179], v[140:141]
	v_pk_mul_f32 v[138:139], v[178:179], v[138:139]
	v_pk_mul_f32 v[136:137], v[178:179], v[136:137]
	v_pk_mul_f32 v[134:135], v[178:179], v[134:135]
	v_pk_mul_f32 v[132:133], v[178:179], v[132:133]
	v_pk_mul_f32 v[130:131], v[178:179], v[130:131]
	v_pk_mul_f32 v[128:129], v[170:171], v[128:129]
	s_nop 1
	s_waitcnt lgkmcnt(4)
	v_readfirstlane_b32 s88, v128
	s_cmp_gt_u32 s88, 0xc35c0000
	s_cselect_b32 s89, 1, 0
	v_mfma_f32_32x32x16_bf16 v[144:159], v[206:209], v[210:213], v[128:143]
	v_add_u32_e32 v226, s44, v192
	ds_read_b128 v[206:209], v226 offset:0
	ds_read_b128 v[210:213], v185 offset:0xc00
	s_waitcnt lgkmcnt(4)
	v_mfma_f32_32x32x16_bf16 v[144:159], v[218:221], v[222:225], v[144:159]
	v_add_u32_e32 v227, s44, v193
	ds_read_b128 v[218:221], v227 offset:0
	ds_read_b128 v[222:225], v185 offset:0x1000
	s_waitcnt lgkmcnt(4)
	v_mfma_f32_32x32x16_bf16 v[144:159], v[242:245], v[246:249], v[144:159]
	v_add_u32_e32 v229, s44, v194
	ds_read_b128 v[242:245], v229 offset:0
	ds_read_b128 v[246:249], v185 offset:0x1400
	s_waitcnt lgkmcnt(4)
	v_mfma_f32_32x32x16_bf16 v[144:159], v[206:209], v[210:213], v[144:159]
	v_add_u32_e32 v230, s44, v195
	ds_read_b128 v[206:209], v230 offset:0
	ds_read_b128 v[210:213], v185 offset:0x1800
	s_waitcnt lgkmcnt(4)
	v_mfma_f32_32x32x16_bf16 v[128:143], v[218:221], v[222:225], v[128:143]
	v_add_u32_e32 v232, s44, v196
	ds_read_b128 v[218:221], v232 offset:0
	ds_read_b128 v[222:225], v185 offset:0x1c00
	s_waitcnt lgkmcnt(4)
	v_mfma_f32_32x32x16_bf16 v[128:143], v[242:245], v[246:249], v[128:143]
	s_waitcnt lgkmcnt(2)
	v_mfma_f32_32x32x16_bf16 v[128:143], v[206:209], v[210:213], v[128:143]
	s_waitcnt lgkmcnt(0)
	v_mfma_f32_32x32x16_bf16 v[128:143], v[218:221], v[222:225], v[128:143]
	s_nop 3
	s_cmp_eq_u32 s89, 0
	s_cbranch_scc1 .Lattn_exp_normal_0_0
	v_max3_f32 v240, v144, v145, v146
	v_max3_f32 v240, v240, v147, v148
	v_max3_f32 v240, v240, v149, v150
	v_max3_f32 v240, v240, v151, v152
	v_max3_f32 v240, v240, v153, v154
	v_max3_f32 v240, v240, v155, v156
	v_max3_f32 v240, v240, v157, v158
	v_max_f32_e32 v240, v240, v159
	v_cmp_ngt_f32_e32 vcc, 0xc3180000, v240
	s_and_b64 vcc, exec, vcc
	s_cbranch_vccnz .Lattn_exp_normal_0_0
	v_mov_b32_e32 v144, 0
	v_mov_b32_e32 v145, 0
	v_mov_b32_e32 v146, 0
	v_mov_b32_e32 v147, 0
	v_mov_b32_e32 v148, 0
	v_mov_b32_e32 v149, 0
	v_mov_b32_e32 v150, 0
	v_mov_b32_e32 v151, 0
	s_branch .Lattn_exp_done_0_0

; #define SCHED() __builtin_amdgcn_sched_barrier(0)
; #define DSR(dst, addr, off) asm volatile("ds_read_b128 %0, %1 offset:%2" : "=&v"(dst) : "v"(addr), "n"(off) : "memory")
; #define LGKM(n) asm volatile("s_waitcnt lgkmcnt(%0)" ::"n"(n) : "memory")
; #define DSR(dst, addr, off) asm volatile("ds_read_b128 %0, %1 offset:%2" : "=&v"(dst) : "v"(addr), "n"(off) : "memory")
; #define LGKM(n) asm volatile("s_waitcnt lgkmcnt(%0)" ::"n"(n) : "memory")
; __device__ __forceinline__ void attn_phase(char* shm, const Params& p, const u16* __restrict__ qb, const u16* __restrict__ kb,
;                                            const u16* __restrict__ vT, u16* __restrict__ attn) {
;     ...
;         for (int c = 0; c < 2; ++c) {
;           f32x16 Sx;
; #pragma unroll
;           for (int i = 0; i < 16; ++i) Sx[i] = -sl2 * fabsf(df + (float)((i & 3) + 8 * (i >> 2)));
; #pragma unroll
;           for (int ks = 0; ks < 4; ++ks) {
;             const int f = c * 4 + ks;
;             if (f < 7) {
;               DSR(kf[(f + 1) & 1], kb_ + (kL0 ^ ((((f + 1) >> 2) * 8 + ((f + 1) & 3) * 2) << 4)), u * 8192);
;               DSR(qf[(f + 1) & 1], qaddr, (f + 1) * 1024);
;               LGKM(2);
;             } else LGKM(0);
;             SCHED();
;             Sx = __builtin_amdgcn_mfma_f32_32x32x16_bf16(kf[f & 1], qf[f & 1], Sx, 0, 0, 0);
;             SCHED();
;           }
;           float pv[16];
; #pragma unroll
;           for (int i = 0; i < 16; ++i) { pv[i] = __builtin_amdgcn_exp2f(Sx[i]); lsum[c] += pv[i]; }
; #pragma unroll
;           for (int a = 0; a < 2; ++a) {
;             i32x4 t4;
; #pragma unroll
;             for (int i = 0; i < 4; ++i) t4[i] = pk_bf16(pv[a * 8 + 2 * i], pv[a * 8 + 2 * i + 1]);
;             P[c][a] = __builtin_bit_cast(bf16x8, t4);
;           }
;         }
.Lattn_exp_done_0_0:
	s_nop 3
	s_cmp_eq_u32 s89, 0
	s_cbranch_scc1 .Lattn_exp_normal_0_1
	v_max3_f32 v240, v128, v129, v130
	v_max3_f32 v240, v240, v131, v132
	v_max3_f32 v240, v240, v133, v134
	v_max3_f32 v240, v240, v135, v136
	v_max3_f32 v240, v240, v137, v138
	v_max3_f32 v240, v240, v139, v140
	v_max3_f32 v240, v240, v141, v142
	v_max_f32_e32 v240, v240, v143
	v_cmp_ngt_f32_e32 vcc, 0xc3180000, v240
	s_and_b64 vcc, exec, vcc
	s_cbranch_vccnz .Lattn_exp_normal_0_1
	v_add_u32_e32 v152, s0, v189
	ds_read_b128 v[136:139], v152 offset:0
	ds_read_b128 v[140:143], v152 offset:0x1000
	v_mov_b32_e32 v128, 0
	v_mov_b32_e32 v129, 0
	v_mov_b32_e32 v130, 0
	v_mov_b32_e32 v131, 0
	v_mov_b32_e32 v132, 0
	v_mov_b32_e32 v133, 0
	v_mov_b32_e32 v134, 0
	v_mov_b32_e32 v135, 0
	s_branch .Lattn_exp_done_0_1

; #define SCHED() __builtin_amdgcn_sched_barrier(0)
; #define DSR(dst, addr, off) asm volatile("ds_read_b128 %0, %1 offset:%2" : "=&v"(dst) : "v"(addr), "n"(off) : "memory")
; #define LGKM(n) asm volatile("s_waitcnt lgkmcnt(%0)" ::"n"(n) : "memory")
; #define DSR(dst, addr, off) asm volatile("ds_read_b128 %0, %1 offset:%2" : "=&v"(dst) : "v"(addr), "n"(off) : "memory")
; #define LGKM(n) asm volatile("s_waitcnt lgkmcnt(%0)" ::"n"(n) : "memory")
; __device__ __forceinline__ void attn_phase(char* shm, const Params& p, const u16* __restrict__ qb, const u16* __restrict__ kb,
;                                            const u16* __restrict__ vT, u16* __restrict__ attn) {
;     ...
;         const float df = (float)(kt * 64 + u * 32 + 4 * hh - qpos);
;         bf16x8 P[2][2];
;         bf16x8 kf[2], qf[2];
;         DSR(kf[0], kb_ + kL0, u * 8192); DSR(qf[0], qaddr, 0);
; #pragma unroll
;         for (int c = 0; c < 2; ++c) {
;           f32x16 Sx;
; #pragma unroll
;           for (int i = 0; i < 16; ++i) Sx[i] = -sl2 * fabsf(df + (float)((i & 3) + 8 * (i >> 2)));
; #pragma unroll
;           for (int ks = 0; ks < 4; ++ks) {
;             const int f = c * 4 + ks;
;             if (f < 7) {
;               DSR(kf[(f + 1) & 1], kb_ + (kL0 ^ ((((f + 1) >> 2) * 8 + ((f + 1) & 3) * 2) << 4)), u * 8192);
;               DSR(qf[(f + 1) & 1], qaddr, (f + 1) * 1024);
;               LGKM(2);
;             } else LGKM(0);
;             SCHED();
;             Sx = __builtin_amdgcn_mfma_f32_32x32x16_bf16(kf[f & 1], qf[f & 1], Sx, 0, 0, 0);
;             SCHED();
;           }
;           float pv[16];
; #pragma unroll
;           for (int i = 0; i < 16; ++i) { pv[i] = __builtin_amdgcn_exp2f(Sx[i]); lsum[c] += pv[i]; }
; #pragma unroll
;           for (int a = 0; a < 2; ++a) {
;             i32x4 t4;
; #pragma unroll
;             for (int i = 0; i < 4; ++i) t4[i] = pk_bf16(pv[a * 8 + 2 * i], pv[a * 8 + 2 * i + 1]);
;             P[c][a] = __builtin_bit_cast(bf16x8, t4);
;           }
;         }
.Lattn_pv_zero_0:
	s_waitcnt lgkmcnt(0)
	v_add_u32_e32 v128, 32, v205
	v_cvt_f32_i32_e32 v128, v128
	ds_read_b128 v[206:209], v160 offset:0x2000
	ds_read_b128 v[210:213], v185 offset:0
	ds_read_b128 v[218:221], v214 offset:0x2000
	ds_read_b128 v[222:225], v185 offset:0x400
	ds_read_b128 v[242:245], v215 offset:0x2000
	ds_read_b128 v[246:249], v185 offset:0x800
	v_add_f32_e32 v129, 1.0, v128
	v_pk_add_f32 v[130:131], v[128:129], s[12:13] op_sel_hi:[0,1]
	v_pk_add_f32 v[132:133], v[128:129], s[14:15] op_sel_hi:[0,1]
	v_pk_add_f32 v[134:135], v[128:129], s[20:21] op_sel_hi:[0,1]
	v_pk_add_f32 v[136:137], v[128:129], s[22:23] op_sel_hi:[0,1]
	v_pk_add_f32 v[138:139], v[128:129], s[24:25] op_sel_hi:[0,1]
	v_pk_add_f32 v[140:141], v[128:129], s[26:27] op_sel_hi:[0,1]
	v_pk_add_f32 v[142:143], v[128:129], s[28:29] op_sel_hi:[0,1]
	v_and_b32_e32 v131, 0x7fffffff, v131
	v_and_b32_e32 v130, 0x7fffffff, v130
	v_and_b32_e32 v133, 0x7fffffff, v133
	v_and_b32_e32 v132, 0x7fffffff, v132
	v_and_b32_e32 v135, 0x7fffffff, v135
	v_and_b32_e32 v134, 0x7fffffff, v134
	v_and_b32_e32 v137, 0x7fffffff, v137
	v_and_b32_e32 v136, 0x7fffffff, v136
	v_and_b32_e32 v139, 0x7fffffff, v139
	v_and_b32_e32 v138, 0x7fffffff, v138
	v_and_b32_e32 v141, 0x7fffffff, v141
	v_and_b32_e32 v140, 0x7fffffff, v140
	v_and_b32_e32 v143, 0x7fffffff, v143
	v_and_b32_e32 v142, 0x7fffffff, v142
	v_and_b32_e32 v128, 0x7fffffff, v128
	v_and_b32_e32 v129, 0x7fffffff, v129
	v_pk_mul_f32 v[142:143], v[178:179], v[142:143]
	v_pk_mul_f32 v[140:141], v[178:179], v[140:141]
	v_pk_mul_f32 v[138:139], v[178:179], v[138:139]
	v_pk_mul_f32 v[136:137], v[178:179], v[136:137]
	v_pk_mul_f32 v[134:135], v[178:179], v[134:135]
	v_pk_mul_f32 v[132:133], v[178:179], v[132:133]
	v_pk_mul_f32 v[130:131], v[178:179], v[130:131]
	v_pk_mul_f32 v[128:129], v[170:171], v[128:129]
	s_nop 1
	s_waitcnt lgkmcnt(4)
	v_readfirstlane_b32 s88, v128
	s_cmp_gt_u32 s88, 0xc35c0000
	s_cselect_b32 s89, 1, 0
	v_mfma_f32_32x32x16_bf16 v[144:159], v[206:209], v[210:213], v[128:143]
	ds_read_b128 v[206:209], v226 offset:0x2000
	ds_read_b128 v[210:213], v185 offset:0xc00
	s_waitcnt lgkmcnt(4)
	v_mfma_f32_32x32x16_bf16 v[144:159], v[218:221], v[222:225], v[144:159]
	ds_read_b128 v[218:221], v227 offset:0x2000
	ds_read_b128 v[222:225], v185 offset:0x1000
	s_waitcnt lgkmcnt(4)
	v_mfma_f32_32x32x16_bf16 v[144:159], v[242:245], v[246:249], v[144:159]
	ds_read_b128 v[242:245], v229 offset:0x2000
	ds_read_b128 v[246:249], v185 offset:0x1400
	s_waitcnt lgkmcnt(4)
	v_mfma_f32_32x32x16_bf16 v[144:159], v[206:209], v[210:213], v[144:159]
	ds_read_b128 v[206:209], v230 offset:0x2000
	ds_read_b128 v[210:213], v185 offset:0x1800
	s_waitcnt lgkmcnt(4)
	v_mfma_f32_32x32x16_bf16 v[128:143], v[218:221], v[222:225], v[128:143]
	ds_read_b128 v[218:221], v232 offset:0x2000
	ds_read_b128 v[222:225], v185 offset:0x1c00
	s_waitcnt lgkmcnt(4)
	v_mfma_f32_32x32x16_bf16 v[128:143], v[242:245], v[246:249], v[128:143]
	s_waitcnt lgkmcnt(2)
	v_mfma_f32_32x32x16_bf16 v[128:143], v[206:209], v[210:213], v[128:143]
	s_waitcnt lgkmcnt(0)
	v_mfma_f32_32x32x16_bf16 v[128:143], v[218:221], v[222:225], v[128:143]
	s_nop 3
	s_cmp_eq_u32 s89, 0
	s_cbranch_scc1 .Lattn_exp_normal_1_0
	v_max3_f32 v240, v144, v145, v146
	v_max3_f32 v240, v240, v147, v148
	v_max3_f32 v240, v240, v149, v150
	v_max3_f32 v240, v240, v151, v152
	v_max3_f32 v240, v240, v153, v154
	v_max3_f32 v240, v240, v155, v156
	v_max3_f32 v240, v240, v157, v158
	v_max_f32_e32 v240, v240, v159
	v_cmp_ngt_f32_e32 vcc, 0xc3180000, v240
	s_and_b64 vcc, exec, vcc
	s_cbranch_vccnz .Lattn_exp_normal_1_0
	v_mov_b32_e32 v144, 0
	v_mov_b32_e32 v145, 0
	v_mov_b32_e32 v146, 0
	v_mov_b32_e32 v147, 0
	v_mov_b32_e32 v148, 0
	v_mov_b32_e32 v149, 0
	v_mov_b32_e32 v150, 0
	v_mov_b32_e32 v151, 0
	s_branch .Lattn_exp_done_1_0

; #define SCHED() __builtin_amdgcn_sched_barrier(0)
; #define DSR(dst, addr, off) asm volatile("ds_read_b128 %0, %1 offset:%2" : "=&v"(dst) : "v"(addr), "n"(off) : "memory")
; #define LGKM(n) asm volatile("s_waitcnt lgkmcnt(%0)" ::"n"(n) : "memory")
; #define DSR(dst, addr, off) asm volatile("ds_read_b128 %0, %1 offset:%2" : "=&v"(dst) : "v"(addr), "n"(off) : "memory")
; #define LGKM(n) asm volatile("s_waitcnt lgkmcnt(%0)" ::"n"(n) : "memory")
; __device__ __forceinline__ void attn_phase(char* shm, const Params& p, const u16* __restrict__ qb, const u16* __restrict__ kb,
;                                            const u16* __restrict__ vT, u16* __restrict__ attn) {
;     ...
;         for (int c = 0; c < 2; ++c) {
;           f32x16 Sx;
; #pragma unroll
;           for (int i = 0; i < 16; ++i) Sx[i] = -sl2 * fabsf(df + (float)((i & 3) + 8 * (i >> 2)));
; #pragma unroll
;           for (int ks = 0; ks < 4; ++ks) {
;             const int f = c * 4 + ks;
;             if (f < 7) {
;               DSR(kf[(f + 1) & 1], kb_ + (kL0 ^ ((((f + 1) >> 2) * 8 + ((f + 1) & 3) * 2) << 4)), u * 8192);
;               DSR(qf[(f + 1) & 1], qaddr, (f + 1) * 1024);
;               LGKM(2);
;             } else LGKM(0);
;             SCHED();
;             Sx = __builtin_amdgcn_mfma_f32_32x32x16_bf16(kf[f & 1], qf[f & 1], Sx, 0, 0, 0);
;             SCHED();
;           }
;           float pv[16];
; #pragma unroll
;           for (int i = 0; i < 16; ++i) { pv[i] = __builtin_amdgcn_exp2f(Sx[i]); lsum[c] += pv[i]; }
; #pragma unroll
;           for (int a = 0; a < 2; ++a) {
;             i32x4 t4;
; #pragma unroll
;             for (int i = 0; i < 4; ++i) t4[i] = pk_bf16(pv[a * 8 + 2 * i], pv[a * 8 + 2 * i + 1]);
;             P[c][a] = __builtin_bit_cast(bf16x8, t4);
;           }
;         }
.Lattn_exp_done_1_0:
	s_nop 3
	s_cmp_eq_u32 s89, 0
	s_cbranch_scc1 .Lattn_exp_normal_1_1
	v_max3_f32 v240, v128, v129, v130
	v_max3_f32 v240, v240, v131, v132
	v_max3_f32 v240, v240, v133, v134
	v_max3_f32 v240, v240, v135, v136
	v_max3_f32 v240, v240, v137, v138
	v_max3_f32 v240, v240, v139, v140
	v_max3_f32 v240, v240, v141, v142
	v_max_f32_e32 v240, v240, v143
	v_cmp_ngt_f32_e32 vcc, 0xc3180000, v240
	s_and_b64 vcc, exec, vcc
	s_cbranch_vccnz .Lattn_exp_normal_1_1
	v_add_u32_e32 v152, s0, v198
	ds_read_b128 v[136:139], v152 offset:0
	ds_read_b128 v[140:143], v152 offset:0x1000
	v_mov_b32_e32 v128, 0
	v_mov_b32_e32 v129, 0
	v_mov_b32_e32 v130, 0
	v_mov_b32_e32 v131, 0
	v_mov_b32_e32 v132, 0
	v_mov_b32_e32 v133, 0
	v_mov_b32_e32 v134, 0
	v_mov_b32_e32 v135, 0
	s_branch .Lattn_exp_done_1_1
